# P3 chain rewrite + hand-written fused diff-attention tile loop (2-deep K/V prefetch, V/P double-buffered in LDS)
# speedup vs baseline: 1.0081x; 1.0024x over previous
; #define LAS __attribute__((address_space(3)))
;     template <bool BG = false>
;     __device__ __forceinline__ void run(LAS unsigned char* lds, f32x16 (&O)[NCOMP][NBLK], BgConv* bg = nullptr) const {
;     ...
;         u32x4 kreg[4], vreg[4];
;         tile_load(kreg, K, ldk, tid); tile_load(vreg, V, ldv, tid);
;         tile_store_k<DH, NCOMP>(kreg, kbuf, tid);
; #pragma unroll
;         for (int c = 0; c < NCOMP; ++c)
; #pragma unroll
;             for (int b = 0; b < NBLK; ++b)
; #pragma unroll
;                 for (int i = 0; i < 16; ++i) O[c][b][i] = 0.f;
;         float lsum = 0.f;
;         f32x4 bgv[4], bgg;
;         __syncthreads();
;         auto body = [&](const int t, auto moret, auto bgt) {
;             constexpr bool more = decltype(moret)::value, BGI = decltype(bgt)::value;
;             if (more) tile_load(kreg, K + (size_t)(64 * (t + 1)) * ldk, ldk, tid);
;             f32x16 st;
; #pragma unroll
;             for (int i = 0; i < 16; ++i) st[i] = 0.f;
;             if (DH == 128) {
;                 bf16x8 kfa[KS];
; #pragma unroll
;                 for (int s = 0; s < KS; ++s) kfa[s] = *(const LAS bf16x8*)(kbuf + ((32 * kh + r) * NCOMP + compA) * KST + (16 * s + 8 * h) * 2);
;                 asm volatile("" ::: "memory");
;                 tile_store_raw(vreg, vbuf, tid);
; #pragma unroll
;                 for (int s = 0; s < KS; ++s) st = MFMA32(kfa[s], qf[s], st);
;             } else {
;             tile_store_raw(vreg, vbuf, tid);
; #pragma unroll
;             for (int s = 0; s < KS; ++s) { const bf16x8 kf = *(const LAS bf16x8*)(kbuf + ((32 * kh + r) * NCOMP + compA) * KST + (16 * s + 8 * h) * 2); st = MFMA32(kf, qf[s], st);
;                 if ((s & 3) == 3) asm volatile("" ::: "memory"); }
;             }
;             float pe[16];
; #pragma unroll
;             for (int i = 0; i < 16; ++i) { pe[i] = fexp2(st[i] - m2); lsum += pe[i]; }
; #pragma unroll
;             for (int g = 0; g < 4; ++g) { u32x2 w; w.x = pk2(pe[4 * g], pe[4 * g + 1]); w.y = pk2(pe[4 * g + 2], pe[4 * g + 3]);
;                 *(LAS u32x2*)(pbuf + ((compA * NRB + rbA) * 32 + r) * PST + (32 * kh + 8 * g + 4 * h) * 2) = w; }
;             __syncthreads();
;             if (more) tile_load(vreg, V + (size_t)(64 * (t + 1)) * ldv, ldv, tid);
; #pragma unroll
;             for (int s = 0; s < 4; ++s) {
;                 bf16x8 pf[NCOMP];
; #pragma unroll
.LBB0_740:
	s_waitcnt vmcnt(0)
	v_mov_b64_e32 v[160:161], v[152:153]
	v_mov_b64_e32 v[178:179], v[154:155]
	v_and_b32_e32 v202, 31, v0
	v_bfe_u32 v203, v0, 5, 1
	v_bfe_u32 v204, v0, 6, 1
	v_bfe_u32 v205, v0, 7, 1
	v_bfe_u32 v206, v0, 8, 1
	v_lshrrev_b32_e32 v207, 3, v0
	v_and_b32_e32 v208, 7, v0
	v_lshlrev_b32_e32 v209, 1, v202
	v_lshl_add_u32 v209, v204, 6, v209
	v_add_u32_e32 v209, v209, v205
	v_mul_u32_u24_e32 v209, 0x110, v209
	v_lshl_add_u32 v156, v203, 4, v209
	v_mul_u32_u24_e32 v209, 0x220, v207
	v_lshl_add_u32 v158, v208, 4, v209
	v_mul_u32_u24_e32 v209, 0x240, v207
	v_lshl_add_u32 v209, v208, 4, v209
	v_add_u32_e32 v174, 0x8800, v209
	v_add_u32_e32 v175, 0xe800, v174
	v_lshl_add_u32 v209, v205, 1, v206
	v_lshl_add_u32 v209, v209, 5, v202
	v_mul_u32_u24_e32 v209, 0x90, v209
	v_lshl_add_u32 v209, v204, 6, v209
	v_lshl_add_u32 v209, v203, 3, v209
	v_add_u32_e32 v176, 0x11800, v209
	v_add_u32_e32 v177, 0xe800, v176
	v_lshl_add_u32 v209, v206, 5, v202
	v_mul_u32_u24_e32 v209, 0x90, v209
	v_lshl_add_u32 v209, v203, 4, v209
	v_add_u32_e32 v180, 0x11800, v209
	v_add_u32_e32 v182, 0xe800, v180
	v_bfe_u32 v210, v0, 2, 2
	v_lshl_add_u32 v210, v203, 3, v210
	v_mul_u32_u24_e32 v210, 0x240, v210
	v_bfe_u32 v211, v0, 6, 2
	v_lshl_add_u32 v210, v211, 7, v210
	v_bfe_u32 v211, v0, 4, 1
	v_lshl_add_u32 v210, v211, 5, v210
	v_and_b32_e32 v211, 3, v0
	v_lshl_add_u32 v210, v211, 3, v210
	v_add_u32_e32 v183, 0x8800, v210
	v_add_u32_e32 v184, 0xe800, v183
	s_add_i32 s16, s87, 1
	s_min_u32 s16, s16, s83
	s_lshl_b32 s16, s16, 6
	v_mad_i64_i32 v[250:251], s[88:89], s16, v166, v[160:161]
	global_load_dwordx4 v[234:237], v[250:251], off
	global_load_dwordx4 v[238:241], v[250:251], off offset:128
	global_load_dwordx4 v[242:245], v[250:251], off offset:256
	global_load_dwordx4 v[246:249], v[250:251], off offset:384
	s_add_i32 s16, s87, 1
	s_min_u32 s16, s16, s83
	s_lshl_b32 s16, s16, 6
	v_mad_i64_i32 v[250:251], s[88:89], s16, v166, v[178:179]
	global_load_dwordx4 v[140:143], v[250:251], off
	global_load_dwordx4 v[144:147], v[250:251], off offset:128
	global_load_dwordx4 v[148:151], v[250:251], off offset:256
	global_load_dwordx4 v[152:155], v[250:251], off offset:384
	s_add_i32 s16, s87, 2
	s_min_u32 s16, s16, s83
	s_lshl_b32 s16, s16, 6
	v_mad_i64_i32 v[250:251], s[88:89], s16, v166, v[160:161]
	global_load_dwordx4 v[186:189], v[250:251], off
	global_load_dwordx4 v[190:193], v[250:251], off offset:128
	global_load_dwordx4 v[194:197], v[250:251], off offset:256
	global_load_dwordx4 v[198:201], v[250:251], off offset:384
	ds_read_b128 v[202:205], v156
	ds_read_b128 v[206:209], v156 offset:32
	ds_read_b128 v[210:213], v156 offset:64
	ds_read_b128 v[214:217], v156 offset:96
	ds_read_b128 v[218:221], v156 offset:128
	ds_read_b128 v[222:225], v156 offset:160
	ds_read_b128 v[226:229], v156 offset:192
	ds_read_b128 v[230:233], v156 offset:224
	ds_write_b128 v174, v[128:131]
	ds_write_b128 v174, v[124:127] offset:128
	ds_write_b128 v174, v[120:123] offset:256
	ds_write_b128 v174, v[116:119] offset:384
	s_waitcnt lgkmcnt(11)
	v_mfma_f32_32x32x16_bf16 v[68:83], v[202:205], v[112:115], 0
	s_waitcnt lgkmcnt(10)
	v_mfma_f32_32x32x16_bf16 v[68:83], v[206:209], v[108:111], v[68:83]
	s_waitcnt lgkmcnt(9)
	v_mfma_f32_32x32x16_bf16 v[68:83], v[210:213], v[104:107], v[68:83]
	s_waitcnt lgkmcnt(8)
	v_mfma_f32_32x32x16_bf16 v[68:83], v[214:217], v[100:103], v[68:83]
	s_waitcnt lgkmcnt(7)
	v_mfma_f32_32x32x16_bf16 v[68:83], v[218:221], v[96:99], v[68:83]
	s_waitcnt lgkmcnt(6)
	v_mfma_f32_32x32x16_bf16 v[68:83], v[222:225], v[92:95], v[68:83]
	s_waitcnt lgkmcnt(5)
	v_mfma_f32_32x32x16_bf16 v[68:83], v[226:229], v[88:91], v[68:83]
	s_waitcnt lgkmcnt(4)
	v_mfma_f32_32x32x16_bf16 v[68:83], v[230:233], v[84:87], v[68:83]
	s_nop 11
	v_sub_f32_e32 v68, v68, v170
	v_sub_f32_e32 v69, v69, v170
	v_sub_f32_e32 v70, v70, v170
	v_sub_f32_e32 v71, v71, v170
	v_sub_f32_e32 v72, v72, v170
	v_sub_f32_e32 v73, v73, v170
	v_sub_f32_e32 v74, v74, v170
	v_sub_f32_e32 v75, v75, v170
	v_sub_f32_e32 v76, v76, v170
	v_sub_f32_e32 v77, v77, v170
	v_sub_f32_e32 v78, v78, v170
	v_sub_f32_e32 v79, v79, v170
	v_sub_f32_e32 v80, v80, v170
	v_sub_f32_e32 v81, v81, v170
	v_sub_f32_e32 v82, v82, v170
	v_sub_f32_e32 v83, v83, v170
	v_exp_f32_e32 v68, v68
	v_exp_f32_e32 v69, v69
	v_exp_f32_e32 v70, v70
	v_exp_f32_e32 v71, v71
	v_exp_f32_e32 v72, v72
	v_exp_f32_e32 v73, v73
	v_exp_f32_e32 v74, v74
	v_exp_f32_e32 v75, v75
	v_exp_f32_e32 v76, v76
	v_exp_f32_e32 v77, v77
	v_exp_f32_e32 v78, v78
	v_exp_f32_e32 v79, v79
	v_exp_f32_e32 v80, v80
	v_exp_f32_e32 v81, v81
	v_exp_f32_e32 v82, v82
	v_exp_f32_e32 v83, v83
	v_cvt_pk_bf16_f32 v132, v68, v69
	v_cvt_pk_bf16_f32 v133, v70, v71
	v_cvt_pk_bf16_f32 v134, v72, v73
	v_cvt_pk_bf16_f32 v135, v74, v75
	v_cvt_pk_bf16_f32 v136, v76, v77
	v_cvt_pk_bf16_f32 v137, v78, v79
	v_cvt_pk_bf16_f32 v138, v80, v81
	v_cvt_pk_bf16_f32 v139, v82, v83
	ds_write2_b64 v176, v[132:133], v[134:135] offset1:2
	ds_write2_b64 v176, v[136:137], v[138:139] offset0:4 offset1:6
	v_add_f32_e32 v181, v181, v68
	v_add_f32_e32 v181, v69, v181
	v_add_f32_e32 v181, v70, v181
	v_add_f32_e32 v181, v71, v181
	v_add_f32_e32 v181, v72, v181
	v_add_f32_e32 v181, v73, v181
	v_add_f32_e32 v181, v74, v181
	v_add_f32_e32 v181, v75, v181
	v_add_f32_e32 v181, v76, v181
	v_add_f32_e32 v181, v77, v181
	v_add_f32_e32 v181, v78, v181
	v_add_f32_e32 v181, v79, v181
	v_add_f32_e32 v181, v80, v181
	v_add_f32_e32 v181, v81, v181
	v_add_f32_e32 v181, v82, v181
	v_add_f32_e32 v181, v83, v181
	s_waitcnt lgkmcnt(0)
	s_barrier
	s_waitcnt vmcnt(8)
	ds_write_b128 v158, v[234:237]
	ds_write_b128 v158, v[238:241] offset:128
	ds_write_b128 v158, v[242:245] offset:272
	ds_write_b128 v158, v[246:249] offset:400
	s_add_i32 s16, s87, 2
	s_min_u32 s16, s16, s83
	s_lshl_b32 s16, s16, 6
	v_mad_i64_i32 v[250:251], s[88:89], s16, v166, v[178:179]
	global_load_dwordx4 v[128:131], v[250:251], off
	global_load_dwordx4 v[124:127], v[250:251], off offset:128
	global_load_dwordx4 v[120:123], v[250:251], off offset:256
	global_load_dwordx4 v[116:119], v[250:251], off offset:384
	s_add_i32 s16, s87, 3
	s_min_u32 s16, s16, s83
	s_lshl_b32 s16, s16, 6
	v_mad_i64_i32 v[250:251], s[88:89], s16, v166, v[160:161]
	global_load_dwordx4 v[234:237], v[250:251], off
	global_load_dwordx4 v[238:241], v[250:251], off offset:128
	global_load_dwordx4 v[242:245], v[250:251], off offset:256
	global_load_dwordx4 v[246:249], v[250:251], off offset:384
	s_waitcnt lgkmcnt(0)
	s_barrier
	s_cmp_lt_u32 s87, s83
	s_cbranch_scc0 .Lfa_fin_s1
;     template <bool BG = false>
;     __device__ __forceinline__ void run(LAS unsigned char* lds, f32x16 (&O)[NCOMP][NBLK], BgConv* bg = nullptr) const {
;     ...
;         auto body = [&](const int t, auto moret, auto bgt) {
;             constexpr bool more = decltype(moret)::value, BGI = decltype(bgt)::value;
;             if (more) tile_load(kreg, K + (size_t)(64 * (t + 1)) * ldk, ldk, tid);
;             f32x16 st;
; #pragma unroll
;             for (int i = 0; i < 16; ++i) st[i] = 0.f;
;             if (DH == 128) {
;                 bf16x8 kfa[KS];
; #pragma unroll
;                 for (int s = 0; s < KS; ++s) kfa[s] = *(const LAS bf16x8*)(kbuf + ((32 * kh + r) * NCOMP + compA) * KST + (16 * s + 8 * h) * 2);
;                 asm volatile("" ::: "memory");
;                 tile_store_raw(vreg, vbuf, tid);
; #pragma unroll
;                 for (int s = 0; s < KS; ++s) st = MFMA32(kfa[s], qf[s], st);
;             } else {
;             tile_store_raw(vreg, vbuf, tid);
; #pragma unroll
;             for (int s = 0; s < KS; ++s) { const bf16x8 kf = *(const LAS bf16x8*)(kbuf + ((32 * kh + r) * NCOMP + compA) * KST + (16 * s + 8 * h) * 2); st = MFMA32(kf, qf[s], st);
;                 if ((s & 3) == 3) asm volatile("" ::: "memory"); }
;             }
;             float pe[16];
; #pragma unroll
;             for (int i = 0; i < 16; ++i) { pe[i] = fexp2(st[i] - m2); lsum += pe[i]; }
; #pragma unroll
;             for (int g = 0; g < 4; ++g) { u32x2 w; w.x = pk2(pe[4 * g], pe[4 * g + 1]); w.y = pk2(pe[4 * g + 2], pe[4 * g + 3]);
;                 *(LAS u32x2*)(pbuf + ((compA * NRB + rbA) * 32 + r) * PST + (32 * kh + 8 * g + 4 * h) * 2) = w; }
;             __syncthreads();
;             if (more) tile_load(vreg, V + (size_t)(64 * (t + 1)) * ldv, ldv, tid);
; #pragma unroll
;             for (int s = 0; s < 4; ++s) {
;                 bf16x8 pf[NCOMP];
; #pragma unroll
;                 for (int c = 0; c < NCOMP; ++c) pf[c] = *(const LAS bf16x8*)(pbuf + ((c * NRB + rbB) * 32 + r) * PST + (16 * s + 8 * h) * 2);
; #pragma unroll
;                 for (int b = 0; b < NBLK; ++b) {
;                     const bf16x8 vf = trfrag(vbuf + (16 * s + 8 * h + q4) * VST + (DVW * dvp + 32 * b + 16 * b16 + 4 * p4) * 2, 4 * VST);
; #pragma unroll
;                     for (int c = 0; c < NCOMP; ++c) O[c][b] = MFMA32(pf[c], vf, O[c][b]);
;                 }
.Lfa_loop_s1:
	ds_read_b128 v[202:205], v156
	ds_read_b128 v[206:209], v156 offset:32
	ds_read_b128 v[210:213], v156 offset:64
	ds_read_b128 v[214:217], v156 offset:96
	ds_read_b128 v[218:221], v156 offset:128
	ds_read_b128 v[222:225], v156 offset:160
	ds_read_b128 v[226:229], v156 offset:192
	ds_read_b128 v[230:233], v156 offset:224
	s_waitcnt vmcnt(12)
	ds_write_b128 v175, v[140:143]
	ds_write_b128 v175, v[144:147] offset:128
	ds_write_b128 v175, v[148:151] offset:256
	ds_write_b128 v175, v[152:155] offset:384
	s_add_i32 s16, s87, 3
	s_min_u32 s16, s16, s83
	s_lshl_b32 s16, s16, 6
	v_mad_i64_i32 v[250:251], s[88:89], s16, v166, v[178:179]
	global_load_dwordx4 v[140:143], v[250:251], off
	global_load_dwordx4 v[144:147], v[250:251], off offset:128
	global_load_dwordx4 v[148:151], v[250:251], off offset:256
	global_load_dwordx4 v[152:155], v[250:251], off offset:384
	s_waitcnt lgkmcnt(11)
	v_mfma_f32_32x32x16_bf16 v[68:83], v[202:205], v[112:115], 0
	s_waitcnt lgkmcnt(10)
	v_mfma_f32_32x32x16_bf16 v[68:83], v[206:209], v[108:111], v[68:83]
	s_waitcnt lgkmcnt(9)
	v_mfma_f32_32x32x16_bf16 v[68:83], v[210:213], v[104:107], v[68:83]
	s_waitcnt lgkmcnt(8)
	v_mfma_f32_32x32x16_bf16 v[68:83], v[214:217], v[100:103], v[68:83]
	s_waitcnt lgkmcnt(7)
	v_mfma_f32_32x32x16_bf16 v[68:83], v[218:221], v[96:99], v[68:83]
	s_waitcnt lgkmcnt(6)
	v_mfma_f32_32x32x16_bf16 v[68:83], v[222:225], v[92:95], v[68:83]
	s_waitcnt lgkmcnt(5)
	v_mfma_f32_32x32x16_bf16 v[68:83], v[226:229], v[88:91], v[68:83]
	s_waitcnt lgkmcnt(4)
	v_mfma_f32_32x32x16_bf16 v[68:83], v[230:233], v[84:87], v[68:83]
	s_barrier
	ds_read_b128 v[218:221], v180
	ds_read_b64_tr_b16 v[226:227], v183
	ds_read_b64_tr_b16 v[228:229], v183 offset:2304
	ds_read_b128 v[222:225], v180 offset:9216
	ds_read_b64_tr_b16 v[230:231], v183 offset:64
	ds_read_b64_tr_b16 v[232:233], v183 offset:2368
	ds_read_b128 v[202:205], v180 offset:32
	ds_read_b64_tr_b16 v[210:211], v183 offset:9216
	ds_read_b64_tr_b16 v[212:213], v183 offset:11520
	ds_read_b128 v[206:209], v180 offset:9248
	ds_read_b64_tr_b16 v[214:215], v183 offset:9280
	ds_read_b64_tr_b16 v[216:217], v183 offset:11584
	s_waitcnt lgkmcnt(9)
	v_mfma_f32_32x32x16_bf16 v[52:67], v[218:221], v[226:229], v[52:67]
	v_sub_f32_e32 v68, v68, v170
	v_sub_f32_e32 v69, v69, v170
	v_sub_f32_e32 v70, v70, v170
	v_sub_f32_e32 v71, v71, v170
	s_waitcnt lgkmcnt(8)
	v_mfma_f32_32x32x16_bf16 v[20:35], v[222:225], v[226:229], v[20:35]
	v_sub_f32_e32 v72, v72, v170
	v_sub_f32_e32 v73, v73, v170
	v_sub_f32_e32 v74, v74, v170
	v_sub_f32_e32 v75, v75, v170
	s_waitcnt lgkmcnt(6)
	v_mfma_f32_32x32x16_bf16 v[36:51], v[218:221], v[230:233], v[36:51]
	v_sub_f32_e32 v76, v76, v170
	v_sub_f32_e32 v77, v77, v170
	v_sub_f32_e32 v78, v78, v170
	v_sub_f32_e32 v79, v79, v170
	v_mfma_f32_32x32x16_bf16 v[4:19], v[222:225], v[230:233], v[4:19]
	v_sub_f32_e32 v80, v80, v170
	v_sub_f32_e32 v81, v81, v170
	v_sub_f32_e32 v82, v82, v170
	v_sub_f32_e32 v83, v83, v170
	ds_read_b128 v[218:221], v180 offset:64
	ds_read_b64_tr_b16 v[226:227], v183 offset:18432
	ds_read_b64_tr_b16 v[228:229], v183 offset:20736
	ds_read_b128 v[222:225], v180 offset:9280
	ds_read_b64_tr_b16 v[230:231], v183 offset:18496
	ds_read_b64_tr_b16 v[232:233], v183 offset:20800
	s_waitcnt lgkmcnt(9)
	v_mfma_f32_32x32x16_bf16 v[52:67], v[202:205], v[210:213], v[52:67]
	v_exp_f32_e32 v68, v68
	v_exp_f32_e32 v69, v69
	v_exp_f32_e32 v70, v70
	v_exp_f32_e32 v71, v71
	s_waitcnt lgkmcnt(8)
	v_mfma_f32_32x32x16_bf16 v[20:35], v[206:209], v[210:213], v[20:35]
	v_exp_f32_e32 v72, v72
	v_exp_f32_e32 v73, v73
	v_exp_f32_e32 v74, v74
	v_exp_f32_e32 v75, v75
	s_waitcnt lgkmcnt(6)
	v_mfma_f32_32x32x16_bf16 v[36:51], v[202:205], v[214:217], v[36:51]
	v_exp_f32_e32 v76, v76
	v_exp_f32_e32 v77, v77
	v_exp_f32_e32 v78, v78
	v_exp_f32_e32 v79, v79
	v_mfma_f32_32x32x16_bf16 v[4:19], v[206:209], v[214:217], v[4:19]
	v_exp_f32_e32 v80, v80
	v_exp_f32_e32 v81, v81
	v_exp_f32_e32 v82, v82
	v_exp_f32_e32 v83, v83
	ds_read_b128 v[202:205], v180 offset:96
	ds_read_b64_tr_b16 v[210:211], v183 offset:27648
	ds_read_b64_tr_b16 v[212:213], v183 offset:29952
	ds_read_b128 v[206:209], v180 offset:9312
	ds_read_b64_tr_b16 v[214:215], v183 offset:27712
	ds_read_b64_tr_b16 v[216:217], v183 offset:30016
	s_waitcnt lgkmcnt(9)
	v_mfma_f32_32x32x16_bf16 v[52:67], v[218:221], v[226:229], v[52:67]
	v_cvt_pk_bf16_f32 v132, v68, v69
	v_cvt_pk_bf16_f32 v133, v70, v71
	v_add_f32_e32 v181, v181, v68
	v_add_f32_e32 v181, v69, v181
	s_waitcnt lgkmcnt(8)
	v_mfma_f32_32x32x16_bf16 v[20:35], v[222:225], v[226:229], v[20:35]
	v_cvt_pk_bf16_f32 v134, v72, v73
	v_cvt_pk_bf16_f32 v135, v74, v75
	v_add_f32_e32 v181, v70, v181
	v_add_f32_e32 v181, v71, v181
	s_waitcnt lgkmcnt(6)
	v_mfma_f32_32x32x16_bf16 v[36:51], v[218:221], v[230:233], v[36:51]
	v_cvt_pk_bf16_f32 v136, v76, v77
	v_cvt_pk_bf16_f32 v137, v78, v79
	v_add_f32_e32 v181, v72, v181
	v_add_f32_e32 v181, v73, v181
	v_mfma_f32_32x32x16_bf16 v[4:19], v[222:225], v[230:233], v[4:19]
	v_cvt_pk_bf16_f32 v138, v80, v81
	v_cvt_pk_bf16_f32 v139, v82, v83
	v_add_f32_e32 v181, v74, v181
	v_add_f32_e32 v181, v75, v181
	ds_write2_b64 v177, v[132:133], v[134:135] offset1:2
	ds_write2_b64 v177, v[136:137], v[138:139] offset0:4 offset1:6
	s_waitcnt lgkmcnt(5)
	v_mfma_f32_32x32x16_bf16 v[52:67], v[202:205], v[210:213], v[52:67]
	v_add_f32_e32 v181, v76, v181
	v_add_f32_e32 v181, v77, v181
	s_waitcnt lgkmcnt(4)
	v_mfma_f32_32x32x16_bf16 v[20:35], v[206:209], v[210:213], v[20:35]
	v_add_f32_e32 v181, v78, v181
	v_add_f32_e32 v181, v79, v181
	s_waitcnt lgkmcnt(2)
	v_mfma_f32_32x32x16_bf16 v[36:51], v[202:205], v[214:217], v[36:51]
	v_add_f32_e32 v181, v80, v181
	v_add_f32_e32 v181, v81, v181
	v_mfma_f32_32x32x16_bf16 v[4:19], v[206:209], v[214:217], v[4:19]
	v_add_f32_e32 v181, v82, v181
	v_add_f32_e32 v181, v83, v181
	s_waitcnt vmcnt(12)
	ds_write_b128 v158, v[186:189]
	ds_write_b128 v158, v[190:193] offset:128
	ds_write_b128 v158, v[194:197] offset:272
	ds_write_b128 v158, v[198:201] offset:400
	s_add_i32 s16, s87, 4
	s_min_u32 s16, s16, s83
	s_lshl_b32 s16, s16, 6
	v_mad_i64_i32 v[250:251], s[88:89], s16, v166, v[160:161]
	global_load_dwordx4 v[186:189], v[250:251], off
	global_load_dwordx4 v[190:193], v[250:251], off offset:128
	global_load_dwordx4 v[194:197], v[250:251], off offset:256
	global_load_dwordx4 v[198:201], v[250:251], off offset:384
	s_waitcnt lgkmcnt(0)
	s_barrier
;     template <bool BG = false>
;     __device__ __forceinline__ void run(LAS unsigned char* lds, f32x16 (&O)[NCOMP][NBLK], BgConv* bg = nullptr) const {
;     ...
;         auto body = [&](const int t, auto moret, auto bgt) {
;             constexpr bool more = decltype(moret)::value, BGI = decltype(bgt)::value;
;             if (more) tile_load(kreg, K + (size_t)(64 * (t + 1)) * ldk, ldk, tid);
;             f32x16 st;
; #pragma unroll
;             for (int i = 0; i < 16; ++i) st[i] = 0.f;
;             if (DH == 128) {
;                 bf16x8 kfa[KS];
; #pragma unroll
;                 for (int s = 0; s < KS; ++s) kfa[s] = *(const LAS bf16x8*)(kbuf + ((32 * kh + r) * NCOMP + compA) * KST + (16 * s + 8 * h) * 2);
;                 asm volatile("" ::: "memory");
;                 tile_store_raw(vreg, vbuf, tid);
; #pragma unroll
;                 for (int s = 0; s < KS; ++s) st = MFMA32(kfa[s], qf[s], st);
;             } else {
;             tile_store_raw(vreg, vbuf, tid);
; #pragma unroll
;             for (int s = 0; s < KS; ++s) { const bf16x8 kf = *(const LAS bf16x8*)(kbuf + ((32 * kh + r) * NCOMP + compA) * KST + (16 * s + 8 * h) * 2); st = MFMA32(kf, qf[s], st);
;                 if ((s & 3) == 3) asm volatile("" ::: "memory"); }
;             }
;             float pe[16];
; #pragma unroll
;             for (int i = 0; i < 16; ++i) { pe[i] = fexp2(st[i] - m2); lsum += pe[i]; }
; #pragma unroll
;             for (int g = 0; g < 4; ++g) { u32x2 w; w.x = pk2(pe[4 * g], pe[4 * g + 1]); w.y = pk2(pe[4 * g + 2], pe[4 * g + 3]);
;                 *(LAS u32x2*)(pbuf + ((compA * NRB + rbA) * 32 + r) * PST + (32 * kh + 8 * g + 4 * h) * 2) = w; }
;             __syncthreads();
;             if (more) tile_load(vreg, V + (size_t)(64 * (t + 1)) * ldv, ldv, tid);
; #pragma unroll
;             for (int s = 0; s < 4; ++s) {
;                 bf16x8 pf[NCOMP];
; #pragma unroll
;                 for (int c = 0; c < NCOMP; ++c) pf[c] = *(const LAS bf16x8*)(pbuf + ((c * NRB + rbB) * 32 + r) * PST + (16 * s + 8 * h) * 2);
; #pragma unroll
;                 for (int b = 0; b < NBLK; ++b) {
;                     const bf16x8 vf = trfrag(vbuf + (16 * s + 8 * h + q4) * VST + (DVW * dvp + 32 * b + 16 * b16 + 4 * p4) * 2, 4 * VST);
; #pragma unroll
;                     for (int c = 0; c < NCOMP; ++c) O[c][b] = MFMA32(pf[c], vf, O[c][b]);
;                 }
	v_swap_b32 v174, v175
	v_swap_b32 v176, v177
	v_swap_b32 v180, v182
	v_swap_b32 v183, v184
	s_add_i32 s87, s87, 1
	s_cmp_lt_u32 s87, s83
	s_cbranch_scc0 .Lfa_fin_s1
	ds_read_b128 v[202:205], v156
	ds_read_b128 v[206:209], v156 offset:32
	ds_read_b128 v[210:213], v156 offset:64
	ds_read_b128 v[214:217], v156 offset:96
	ds_read_b128 v[218:221], v156 offset:128
	ds_read_b128 v[222:225], v156 offset:160
	ds_read_b128 v[226:229], v156 offset:192
	ds_read_b128 v[230:233], v156 offset:224
	s_waitcnt vmcnt(12)
	ds_write_b128 v175, v[128:131]
	ds_write_b128 v175, v[124:127] offset:128
	ds_write_b128 v175, v[120:123] offset:256
	ds_write_b128 v175, v[116:119] offset:384
	s_add_i32 s16, s87, 3
	s_min_u32 s16, s16, s83
	s_lshl_b32 s16, s16, 6
	v_mad_i64_i32 v[250:251], s[88:89], s16, v166, v[178:179]
	global_load_dwordx4 v[128:131], v[250:251], off
	global_load_dwordx4 v[124:127], v[250:251], off offset:128
	global_load_dwordx4 v[120:123], v[250:251], off offset:256
	global_load_dwordx4 v[116:119], v[250:251], off offset:384
	s_waitcnt lgkmcnt(11)
	v_mfma_f32_32x32x16_bf16 v[68:83], v[202:205], v[112:115], 0
	s_waitcnt lgkmcnt(10)
	v_mfma_f32_32x32x16_bf16 v[68:83], v[206:209], v[108:111], v[68:83]
	s_waitcnt lgkmcnt(9)
	v_mfma_f32_32x32x16_bf16 v[68:83], v[210:213], v[104:107], v[68:83]
	s_waitcnt lgkmcnt(8)
	v_mfma_f32_32x32x16_bf16 v[68:83], v[214:217], v[100:103], v[68:83]
	s_waitcnt lgkmcnt(7)
	v_mfma_f32_32x32x16_bf16 v[68:83], v[218:221], v[96:99], v[68:83]
	s_waitcnt lgkmcnt(6)
	v_mfma_f32_32x32x16_bf16 v[68:83], v[222:225], v[92:95], v[68:83]
	s_waitcnt lgkmcnt(5)
	v_mfma_f32_32x32x16_bf16 v[68:83], v[226:229], v[88:91], v[68:83]
	s_waitcnt lgkmcnt(4)
	v_mfma_f32_32x32x16_bf16 v[68:83], v[230:233], v[84:87], v[68:83]
	s_barrier
	ds_read_b128 v[218:221], v180
	ds_read_b64_tr_b16 v[226:227], v183
	ds_read_b64_tr_b16 v[228:229], v183 offset:2304
	ds_read_b128 v[222:225], v180 offset:9216
	ds_read_b64_tr_b16 v[230:231], v183 offset:64
	ds_read_b64_tr_b16 v[232:233], v183 offset:2368
	ds_read_b128 v[202:205], v180 offset:32
	ds_read_b64_tr_b16 v[210:211], v183 offset:9216
	ds_read_b64_tr_b16 v[212:213], v183 offset:11520
	ds_read_b128 v[206:209], v180 offset:9248
	ds_read_b64_tr_b16 v[214:215], v183 offset:9280
	ds_read_b64_tr_b16 v[216:217], v183 offset:11584
	s_waitcnt lgkmcnt(9)
	v_mfma_f32_32x32x16_bf16 v[52:67], v[218:221], v[226:229], v[52:67]
	v_sub_f32_e32 v68, v68, v170
	v_sub_f32_e32 v69, v69, v170
	v_sub_f32_e32 v70, v70, v170
	v_sub_f32_e32 v71, v71, v170
	s_waitcnt lgkmcnt(8)
	v_mfma_f32_32x32x16_bf16 v[20:35], v[222:225], v[226:229], v[20:35]
	v_sub_f32_e32 v72, v72, v170
	v_sub_f32_e32 v73, v73, v170
	v_sub_f32_e32 v74, v74, v170
	v_sub_f32_e32 v75, v75, v170
	s_waitcnt lgkmcnt(6)
	v_mfma_f32_32x32x16_bf16 v[36:51], v[218:221], v[230:233], v[36:51]
	v_sub_f32_e32 v76, v76, v170
	v_sub_f32_e32 v77, v77, v170
	v_sub_f32_e32 v78, v78, v170
	v_sub_f32_e32 v79, v79, v170
	v_mfma_f32_32x32x16_bf16 v[4:19], v[222:225], v[230:233], v[4:19]
	v_sub_f32_e32 v80, v80, v170
	v_sub_f32_e32 v81, v81, v170
	v_sub_f32_e32 v82, v82, v170
	v_sub_f32_e32 v83, v83, v170
	ds_read_b128 v[218:221], v180 offset:64
	ds_read_b64_tr_b16 v[226:227], v183 offset:18432
	ds_read_b64_tr_b16 v[228:229], v183 offset:20736
	ds_read_b128 v[222:225], v180 offset:9280
	ds_read_b64_tr_b16 v[230:231], v183 offset:18496
	ds_read_b64_tr_b16 v[232:233], v183 offset:20800
	s_waitcnt lgkmcnt(9)
	v_mfma_f32_32x32x16_bf16 v[52:67], v[202:205], v[210:213], v[52:67]
	v_exp_f32_e32 v68, v68
	v_exp_f32_e32 v69, v69
	v_exp_f32_e32 v70, v70
	v_exp_f32_e32 v71, v71
	s_waitcnt lgkmcnt(8)
	v_mfma_f32_32x32x16_bf16 v[20:35], v[206:209], v[210:213], v[20:35]
	v_exp_f32_e32 v72, v72
	v_exp_f32_e32 v73, v73
	v_exp_f32_e32 v74, v74
	v_exp_f32_e32 v75, v75
	s_waitcnt lgkmcnt(6)
	v_mfma_f32_32x32x16_bf16 v[36:51], v[202:205], v[214:217], v[36:51]
	v_exp_f32_e32 v76, v76
	v_exp_f32_e32 v77, v77
	v_exp_f32_e32 v78, v78
	v_exp_f32_e32 v79, v79
	v_mfma_f32_32x32x16_bf16 v[4:19], v[206:209], v[214:217], v[4:19]
	v_exp_f32_e32 v80, v80
	v_exp_f32_e32 v81, v81
	v_exp_f32_e32 v82, v82
	v_exp_f32_e32 v83, v83
	ds_read_b128 v[202:205], v180 offset:96
	ds_read_b64_tr_b16 v[210:211], v183 offset:27648
	ds_read_b64_tr_b16 v[212:213], v183 offset:29952
	ds_read_b128 v[206:209], v180 offset:9312
	ds_read_b64_tr_b16 v[214:215], v183 offset:27712
	ds_read_b64_tr_b16 v[216:217], v183 offset:30016
	s_waitcnt lgkmcnt(9)
	v_mfma_f32_32x32x16_bf16 v[52:67], v[218:221], v[226:229], v[52:67]
	v_cvt_pk_bf16_f32 v132, v68, v69
	v_cvt_pk_bf16_f32 v133, v70, v71
	v_add_f32_e32 v181, v181, v68
	v_add_f32_e32 v181, v69, v181
	s_waitcnt lgkmcnt(8)
	v_mfma_f32_32x32x16_bf16 v[20:35], v[222:225], v[226:229], v[20:35]
	v_cvt_pk_bf16_f32 v134, v72, v73
	v_cvt_pk_bf16_f32 v135, v74, v75
	v_add_f32_e32 v181, v70, v181
	v_add_f32_e32 v181, v71, v181
	s_waitcnt lgkmcnt(6)
	v_mfma_f32_32x32x16_bf16 v[36:51], v[218:221], v[230:233], v[36:51]
	v_cvt_pk_bf16_f32 v136, v76, v77
	v_cvt_pk_bf16_f32 v137, v78, v79
	v_add_f32_e32 v181, v72, v181
	v_add_f32_e32 v181, v73, v181
	v_mfma_f32_32x32x16_bf16 v[4:19], v[222:225], v[230:233], v[4:19]
	v_cvt_pk_bf16_f32 v138, v80, v81
	v_cvt_pk_bf16_f32 v139, v82, v83
	v_add_f32_e32 v181, v74, v181
	v_add_f32_e32 v181, v75, v181
	ds_write2_b64 v177, v[132:133], v[134:135] offset1:2
	ds_write2_b64 v177, v[136:137], v[138:139] offset0:4 offset1:6
	s_waitcnt lgkmcnt(5)
	v_mfma_f32_32x32x16_bf16 v[52:67], v[202:205], v[210:213], v[52:67]
	v_add_f32_e32 v181, v76, v181
	v_add_f32_e32 v181, v77, v181
	s_waitcnt lgkmcnt(4)
	v_mfma_f32_32x32x16_bf16 v[20:35], v[206:209], v[210:213], v[20:35]
	v_add_f32_e32 v181, v78, v181
	v_add_f32_e32 v181, v79, v181
	s_waitcnt lgkmcnt(2)
	v_mfma_f32_32x32x16_bf16 v[36:51], v[202:205], v[214:217], v[36:51]
	v_add_f32_e32 v181, v80, v181
	v_add_f32_e32 v181, v81, v181
	v_mfma_f32_32x32x16_bf16 v[4:19], v[206:209], v[214:217], v[4:19]
	v_add_f32_e32 v181, v82, v181
	v_add_f32_e32 v181, v83, v181
	s_waitcnt vmcnt(12)
	ds_write_b128 v158, v[234:237]
	ds_write_b128 v158, v[238:241] offset:128
	ds_write_b128 v158, v[242:245] offset:272
	ds_write_b128 v158, v[246:249] offset:400
	s_add_i32 s16, s87, 4
	s_min_u32 s16, s16, s83
	s_lshl_b32 s16, s16, 6
	v_mad_i64_i32 v[250:251], s[88:89], s16, v166, v[160:161]
	global_load_dwordx4 v[234:237], v[250:251], off
	global_load_dwordx4 v[238:241], v[250:251], off offset:128
	global_load_dwordx4 v[242:245], v[250:251], off offset:256
	global_load_dwordx4 v[246:249], v[250:251], off offset:384
	s_waitcnt lgkmcnt(0)
	s_barrier
	v_swap_b32 v174, v175
	v_swap_b32 v176, v177
	v_swap_b32 v180, v182
	v_swap_b32 v183, v184
	s_add_i32 s87, s87, 1
	s_cmp_lt_u32 s87, s83
	s_cbranch_scc1 .Lfa_loop_s1
; #define LAS __attribute__((address_space(3)))
; #define MFMA32(a, b, c) __builtin_amdgcn_mfma_f32_32x32x16_bf16((a), (b), (c), 0, 0, 0)
;     template <bool BG = false>
;     __device__ __forceinline__ void run(LAS unsigned char* lds, f32x16 (&O)[NCOMP][NBLK], BgConv* bg = nullptr) const {
;     ...
;             for (int s = 0; s < 4; ++s) {
;                 bf16x8 pf[NCOMP];
; #pragma unroll
;                 for (int c = 0; c < NCOMP; ++c) pf[c] = *(const LAS bf16x8*)(pbuf + ((c * NRB + rbB) * 32 + r) * PST + (16 * s + 8 * h) * 2);
; #pragma unroll
;                 for (int b = 0; b < NBLK; ++b) {
;                     const bf16x8 vf = trfrag(vbuf + (16 * s + 8 * h + q4) * VST + (DVW * dvp + 32 * b + 16 * b16 + 4 * p4) * 2, 4 * VST);
; #pragma unroll
;                     for (int c = 0; c < NCOMP; ++c) O[c][b] = MFMA32(pf[c], vf, O[c][b]);
;                 }
;                 asm volatile("" ::: "memory");
;                 if (DH == 128 && s == 1) { if (more) tile_store_k<DH, NCOMP>(kreg, kbuf, tid); }
;             }
;             if (DH != 128) { if (more) tile_store_k<DH, NCOMP>(kreg, kbuf, tid); }
;             if constexpr (BGI) { bg_store(*bg, bgv, bgg, lane); bg->h += bg->step; bg_load(*bg, bgv, bgg, lane); }
;             __syncthreads();
;         };
;         int t = 0;
;         if constexpr (BG) {
;             int n = 0; if (bg->h < BG_NH) { n = (BG_NH - 1 - bg->h) / bg->step + 1; const int fit = (ntiles - 1) / 2; n = (n < fit) ? n : fit; }
;             if (n > 0) { bg_load(*bg, bgv, bgg, lane);
; #pragma unroll 1
;                 for (int g = 0; g < n; ++g, t += 2) { body(t, BoolT<true>{}, BoolT<false>{}); body(t + 1, BoolT<true>{}, BoolT<true>{}); } } }
;         for (; t < ntiles - 1; ++t) body(t, BoolT<true>{}, BoolT<false>{});
;         body(ntiles - 1, BoolT<false>{}, BoolT<false>{});
;         lsum += __shfl_xor(lsum, 32);
;         if (h == 0) lbuf[((compA * NRB + rbA) * 2 + kh) * 32 + r] = lsum;
.Lfa_fin_s1:
	ds_read_b128 v[218:221], v180
	ds_read_b64_tr_b16 v[226:227], v183
	ds_read_b64_tr_b16 v[228:229], v183 offset:2304
	ds_read_b128 v[222:225], v180 offset:9216
	ds_read_b64_tr_b16 v[230:231], v183 offset:64
	ds_read_b64_tr_b16 v[232:233], v183 offset:2368
	ds_read_b128 v[202:205], v180 offset:32
	ds_read_b64_tr_b16 v[210:211], v183 offset:9216
	ds_read_b64_tr_b16 v[212:213], v183 offset:11520
	ds_read_b128 v[206:209], v180 offset:9248
	ds_read_b64_tr_b16 v[214:215], v183 offset:9280
	ds_read_b64_tr_b16 v[216:217], v183 offset:11584
	s_waitcnt lgkmcnt(9)
	v_mfma_f32_32x32x16_bf16 v[52:67], v[218:221], v[226:229], v[52:67]
	s_waitcnt lgkmcnt(8)
	v_mfma_f32_32x32x16_bf16 v[20:35], v[222:225], v[226:229], v[20:35]
	s_waitcnt lgkmcnt(6)
	v_mfma_f32_32x32x16_bf16 v[36:51], v[218:221], v[230:233], v[36:51]
	v_mfma_f32_32x32x16_bf16 v[4:19], v[222:225], v[230:233], v[4:19]
	ds_read_b128 v[218:221], v180 offset:64
	ds_read_b64_tr_b16 v[226:227], v183 offset:18432
	ds_read_b64_tr_b16 v[228:229], v183 offset:20736
	ds_read_b128 v[222:225], v180 offset:9280
	ds_read_b64_tr_b16 v[230:231], v183 offset:18496
	ds_read_b64_tr_b16 v[232:233], v183 offset:20800
	s_waitcnt lgkmcnt(9)
	v_mfma_f32_32x32x16_bf16 v[52:67], v[202:205], v[210:213], v[52:67]
	s_waitcnt lgkmcnt(8)
	v_mfma_f32_32x32x16_bf16 v[20:35], v[206:209], v[210:213], v[20:35]
	s_waitcnt lgkmcnt(6)
	v_mfma_f32_32x32x16_bf16 v[36:51], v[202:205], v[214:217], v[36:51]
	v_mfma_f32_32x32x16_bf16 v[4:19], v[206:209], v[214:217], v[4:19]
	ds_read_b128 v[202:205], v180 offset:96
	ds_read_b64_tr_b16 v[210:211], v183 offset:27648
	ds_read_b64_tr_b16 v[212:213], v183 offset:29952
	ds_read_b128 v[206:209], v180 offset:9312
	ds_read_b64_tr_b16 v[214:215], v183 offset:27712
	ds_read_b64_tr_b16 v[216:217], v183 offset:30016
	s_waitcnt lgkmcnt(9)
	v_mfma_f32_32x32x16_bf16 v[52:67], v[218:221], v[226:229], v[52:67]
	s_waitcnt lgkmcnt(8)
	v_mfma_f32_32x32x16_bf16 v[20:35], v[222:225], v[226:229], v[20:35]
	s_waitcnt lgkmcnt(6)
	v_mfma_f32_32x32x16_bf16 v[36:51], v[218:221], v[230:233], v[36:51]
	v_mfma_f32_32x32x16_bf16 v[4:19], v[222:225], v[230:233], v[4:19]
	s_waitcnt lgkmcnt(3)
	v_mfma_f32_32x32x16_bf16 v[52:67], v[202:205], v[210:213], v[52:67]
	s_waitcnt lgkmcnt(2)
	v_mfma_f32_32x32x16_bf16 v[20:35], v[206:209], v[210:213], v[20:35]
	s_waitcnt lgkmcnt(0)
	v_mfma_f32_32x32x16_bf16 v[36:51], v[202:205], v[214:217], v[36:51]
	v_mfma_f32_32x32x16_bf16 v[4:19], v[206:209], v[214:217], v[4:19]
	s_waitcnt vmcnt(0)
	s_nop 15
	v_mov_b32_e32 v2, v181
	v_xor_b32_e32 v68, 32, v157
	v_cmp_lt_i32_e32 vcc, v68, v162
	s_nop 1
	v_cndmask_b32_e32 v68, v157, v68, vcc
	v_lshlrev_b32_e32 v170, 2, v68
	ds_bpermute_b32 v68, v170, v2
	v_cmp_gt_u32_e32 vcc, 32, v173
	s_and_saveexec_b64 s[36:37], vcc
	s_cbranch_execz .LBB0_749
	s_lshl_b32 s16, s79, 2
	s_lshl_b32 s79, s81, 1
	s_add_i32 s16, s16, s79
	s_or_b32 s16, s16, s84
	s_lshl_b32 s16, s16, 7
	s_add_i32 s16, s16, 0
	v_lshl_add_u32 v69, v171, 2, s16
	v_add_u32_e32 v69, 0x16800, v69
	s_waitcnt lgkmcnt(0)
	v_add_f32_e32 v2, v2, v68
	ds_write_b32 v69, v2

; #define LAS __attribute__((address_space(3)))
;     template <bool BG = false>
;     __device__ __forceinline__ void run(LAS unsigned char* lds, f32x16 (&O)[NCOMP][NBLK], BgConv* bg = nullptr) const {
;     ...
;         u32x4 kreg[4], vreg[4];
;         tile_load(kreg, K, ldk, tid); tile_load(vreg, V, ldv, tid);
;         tile_store_k<DH, NCOMP>(kreg, kbuf, tid);
; #pragma unroll
;         for (int c = 0; c < NCOMP; ++c)
; #pragma unroll
;             for (int b = 0; b < NBLK; ++b)
; #pragma unroll
;                 for (int i = 0; i < 16; ++i) O[c][b][i] = 0.f;
;         float lsum = 0.f;
;         f32x4 bgv[4], bgg;
;         __syncthreads();
;         auto body = [&](const int t, auto moret, auto bgt) {
;             constexpr bool more = decltype(moret)::value, BGI = decltype(bgt)::value;
;             if (more) tile_load(kreg, K + (size_t)(64 * (t + 1)) * ldk, ldk, tid);
;             f32x16 st;
; #pragma unroll
;             for (int i = 0; i < 16; ++i) st[i] = 0.f;
;             if (DH == 128) {
;                 bf16x8 kfa[KS];
; #pragma unroll
;                 for (int s = 0; s < KS; ++s) kfa[s] = *(const LAS bf16x8*)(kbuf + ((32 * kh + r) * NCOMP + compA) * KST + (16 * s + 8 * h) * 2);
;                 asm volatile("" ::: "memory");
;                 tile_store_raw(vreg, vbuf, tid);
; #pragma unroll
;                 for (int s = 0; s < KS; ++s) st = MFMA32(kfa[s], qf[s], st);
;             } else {
;             tile_store_raw(vreg, vbuf, tid);
; #pragma unroll
;             for (int s = 0; s < KS; ++s) { const bf16x8 kf = *(const LAS bf16x8*)(kbuf + ((32 * kh + r) * NCOMP + compA) * KST + (16 * s + 8 * h) * 2); st = MFMA32(kf, qf[s], st);
;                 if ((s & 3) == 3) asm volatile("" ::: "memory"); }
;             }
;             float pe[16];
; #pragma unroll
;             for (int i = 0; i < 16; ++i) { pe[i] = fexp2(st[i] - m2); lsum += pe[i]; }
; #pragma unroll
;             for (int g = 0; g < 4; ++g) { u32x2 w; w.x = pk2(pe[4 * g], pe[4 * g + 1]); w.y = pk2(pe[4 * g + 2], pe[4 * g + 3]);
;                 *(LAS u32x2*)(pbuf + ((compA * NRB + rbA) * 32 + r) * PST + (32 * kh + 8 * g + 4 * h) * 2) = w; }
;             __syncthreads();
;             if (more) tile_load(vreg, V + (size_t)(64 * (t + 1)) * ldv, ldv, tid);
; #pragma unroll
;             for (int s = 0; s < 4; ++s) {
;                 bf16x8 pf[NCOMP];
; #pragma unroll
.LBB0_768:
	s_waitcnt vmcnt(0)
	v_mov_b64_e32 v[160:161], v[152:153]
	v_mov_b64_e32 v[178:179], v[154:155]
	v_and_b32_e32 v202, 31, v0
	v_bfe_u32 v203, v0, 5, 1
	v_bfe_u32 v204, v0, 6, 1
	v_bfe_u32 v205, v0, 7, 1
	v_bfe_u32 v206, v0, 8, 1
	v_lshrrev_b32_e32 v207, 3, v0
	v_and_b32_e32 v208, 7, v0
	v_lshlrev_b32_e32 v209, 1, v202
	v_lshl_add_u32 v209, v204, 6, v209
	v_add_u32_e32 v209, v209, v205
	v_mul_u32_u24_e32 v209, 0x110, v209
	v_lshl_add_u32 v156, v203, 4, v209
	v_mul_u32_u24_e32 v209, 0x220, v207
	v_lshl_add_u32 v158, v208, 4, v209
	v_mul_u32_u24_e32 v209, 0x240, v207
	v_lshl_add_u32 v209, v208, 4, v209
	v_add_u32_e32 v173, 0x8800, v209
	v_add_u32_e32 v175, 0xe800, v173
	v_lshl_add_u32 v209, v205, 1, v206
	v_lshl_add_u32 v209, v209, 5, v202
	v_mul_u32_u24_e32 v209, 0x90, v209
	v_lshl_add_u32 v209, v204, 6, v209
	v_lshl_add_u32 v209, v203, 3, v209
	v_add_u32_e32 v176, 0x11800, v209
	v_add_u32_e32 v177, 0xe800, v176
	v_lshl_add_u32 v209, v206, 5, v202
	v_mul_u32_u24_e32 v209, 0x90, v209
	v_lshl_add_u32 v209, v203, 4, v209
	v_add_u32_e32 v180, 0x11800, v209
	v_add_u32_e32 v181, 0xe800, v180
	v_bfe_u32 v210, v0, 2, 2
	v_lshl_add_u32 v210, v203, 3, v210
	v_mul_u32_u24_e32 v210, 0x240, v210
	v_bfe_u32 v211, v0, 6, 2
	v_lshl_add_u32 v210, v211, 7, v210
	v_bfe_u32 v211, v0, 4, 1
	v_lshl_add_u32 v210, v211, 5, v210
	v_and_b32_e32 v211, 3, v0
	v_lshl_add_u32 v210, v211, 3, v210
	v_add_u32_e32 v183, 0x8800, v210
	v_add_u32_e32 v184, 0xe800, v183
	s_add_i32 s16, s74, 1
	s_min_u32 s16, s16, s73
	s_lshl_b32 s16, s16, 6
	v_mad_i64_i32 v[250:251], s[76:77], s16, v166, v[160:161]
	global_load_dwordx4 v[234:237], v[250:251], off
	global_load_dwordx4 v[238:241], v[250:251], off offset:128
	global_load_dwordx4 v[242:245], v[250:251], off offset:256
	global_load_dwordx4 v[246:249], v[250:251], off offset:384
	s_add_i32 s16, s74, 1
	s_min_u32 s16, s16, s73
	s_lshl_b32 s16, s16, 6
	v_mad_i64_i32 v[250:251], s[76:77], s16, v166, v[178:179]
	global_load_dwordx4 v[140:143], v[250:251], off
	global_load_dwordx4 v[144:147], v[250:251], off offset:128
	global_load_dwordx4 v[148:151], v[250:251], off offset:256
	global_load_dwordx4 v[152:155], v[250:251], off offset:384
	s_add_i32 s16, s74, 2
	s_min_u32 s16, s16, s73
	s_lshl_b32 s16, s16, 6
	v_mad_i64_i32 v[250:251], s[76:77], s16, v166, v[160:161]
	global_load_dwordx4 v[186:189], v[250:251], off
	global_load_dwordx4 v[190:193], v[250:251], off offset:128
	global_load_dwordx4 v[194:197], v[250:251], off offset:256
	global_load_dwordx4 v[198:201], v[250:251], off offset:384
	ds_read_b128 v[202:205], v156
	ds_read_b128 v[206:209], v156 offset:32
	ds_read_b128 v[210:213], v156 offset:64
	ds_read_b128 v[214:217], v156 offset:96
	ds_read_b128 v[218:221], v156 offset:128
	ds_read_b128 v[222:225], v156 offset:160
	ds_read_b128 v[226:229], v156 offset:192
	ds_read_b128 v[230:233], v156 offset:224
	ds_write_b128 v173, v[128:131]
	ds_write_b128 v173, v[124:127] offset:128
	ds_write_b128 v173, v[120:123] offset:256
	ds_write_b128 v173, v[116:119] offset:384
	s_waitcnt lgkmcnt(11)
	v_mfma_f32_32x32x16_bf16 v[68:83], v[202:205], v[112:115], 0
	s_waitcnt lgkmcnt(10)
	v_mfma_f32_32x32x16_bf16 v[68:83], v[206:209], v[108:111], v[68:83]
	s_waitcnt lgkmcnt(9)
	v_mfma_f32_32x32x16_bf16 v[68:83], v[210:213], v[104:107], v[68:83]
	s_waitcnt lgkmcnt(8)
	v_mfma_f32_32x32x16_bf16 v[68:83], v[214:217], v[100:103], v[68:83]
	s_waitcnt lgkmcnt(7)
	v_mfma_f32_32x32x16_bf16 v[68:83], v[218:221], v[96:99], v[68:83]
	s_waitcnt lgkmcnt(6)
	v_mfma_f32_32x32x16_bf16 v[68:83], v[222:225], v[92:95], v[68:83]
	s_waitcnt lgkmcnt(5)
	v_mfma_f32_32x32x16_bf16 v[68:83], v[226:229], v[88:91], v[68:83]
	s_waitcnt lgkmcnt(4)
	v_mfma_f32_32x32x16_bf16 v[68:83], v[230:233], v[84:87], v[68:83]
	s_nop 11
	v_sub_f32_e32 v68, v68, v172
	v_sub_f32_e32 v69, v69, v172
	v_sub_f32_e32 v70, v70, v172
	v_sub_f32_e32 v71, v71, v172
	v_sub_f32_e32 v72, v72, v172
	v_sub_f32_e32 v73, v73, v172
	v_sub_f32_e32 v74, v74, v172
	v_sub_f32_e32 v75, v75, v172
	v_sub_f32_e32 v76, v76, v172
	v_sub_f32_e32 v77, v77, v172
	v_sub_f32_e32 v78, v78, v172
	v_sub_f32_e32 v79, v79, v172
	v_sub_f32_e32 v80, v80, v172
	v_sub_f32_e32 v81, v81, v172
	v_sub_f32_e32 v82, v82, v172
	v_sub_f32_e32 v83, v83, v172
	v_exp_f32_e32 v68, v68
	v_exp_f32_e32 v69, v69
	v_exp_f32_e32 v70, v70
	v_exp_f32_e32 v71, v71
	v_exp_f32_e32 v72, v72
	v_exp_f32_e32 v73, v73
	v_exp_f32_e32 v74, v74
	v_exp_f32_e32 v75, v75
	v_exp_f32_e32 v76, v76
	v_exp_f32_e32 v77, v77
	v_exp_f32_e32 v78, v78
	v_exp_f32_e32 v79, v79
	v_exp_f32_e32 v80, v80
	v_exp_f32_e32 v81, v81
	v_exp_f32_e32 v82, v82
	v_exp_f32_e32 v83, v83
	v_cvt_pk_bf16_f32 v132, v68, v69
	v_cvt_pk_bf16_f32 v133, v70, v71
	v_cvt_pk_bf16_f32 v134, v72, v73
	v_cvt_pk_bf16_f32 v135, v74, v75
	v_cvt_pk_bf16_f32 v136, v76, v77
	v_cvt_pk_bf16_f32 v137, v78, v79
	v_cvt_pk_bf16_f32 v138, v80, v81
	v_cvt_pk_bf16_f32 v139, v82, v83
	ds_write2_b64 v176, v[132:133], v[134:135] offset1:2
	ds_write2_b64 v176, v[136:137], v[138:139] offset0:4 offset1:6
	v_add_f32_e32 v182, v182, v68
	v_add_f32_e32 v182, v69, v182
	v_add_f32_e32 v182, v70, v182
	v_add_f32_e32 v182, v71, v182
	v_add_f32_e32 v182, v72, v182
	v_add_f32_e32 v182, v73, v182
	v_add_f32_e32 v182, v74, v182
	v_add_f32_e32 v182, v75, v182
	v_add_f32_e32 v182, v76, v182
	v_add_f32_e32 v182, v77, v182
	v_add_f32_e32 v182, v78, v182
	v_add_f32_e32 v182, v79, v182
	v_add_f32_e32 v182, v80, v182
	v_add_f32_e32 v182, v81, v182
	v_add_f32_e32 v182, v82, v182
	v_add_f32_e32 v182, v83, v182
	s_waitcnt lgkmcnt(0)
	s_barrier
	s_waitcnt vmcnt(8)
	ds_write_b128 v158, v[234:237]
	ds_write_b128 v158, v[238:241] offset:128
	ds_write_b128 v158, v[242:245] offset:272
	ds_write_b128 v158, v[246:249] offset:400
	s_add_i32 s16, s74, 2
	s_min_u32 s16, s16, s73
	s_lshl_b32 s16, s16, 6
	v_mad_i64_i32 v[250:251], s[76:77], s16, v166, v[178:179]
	global_load_dwordx4 v[128:131], v[250:251], off
	global_load_dwordx4 v[124:127], v[250:251], off offset:128
	global_load_dwordx4 v[120:123], v[250:251], off offset:256
	global_load_dwordx4 v[116:119], v[250:251], off offset:384
	s_add_i32 s16, s74, 3
	s_min_u32 s16, s16, s73
	s_lshl_b32 s16, s16, 6
	v_mad_i64_i32 v[250:251], s[76:77], s16, v166, v[160:161]
	global_load_dwordx4 v[234:237], v[250:251], off
	global_load_dwordx4 v[238:241], v[250:251], off offset:128
	global_load_dwordx4 v[242:245], v[250:251], off offset:256
	global_load_dwordx4 v[246:249], v[250:251], off offset:384
	s_waitcnt lgkmcnt(0)
	s_barrier
	s_cmp_lt_u32 s74, s73
	s_cbranch_scc0 .Lfa_fin_s2
;     template <bool BG = false>
;     __device__ __forceinline__ void run(LAS unsigned char* lds, f32x16 (&O)[NCOMP][NBLK], BgConv* bg = nullptr) const {
;     ...
;         auto body = [&](const int t, auto moret, auto bgt) {
;             constexpr bool more = decltype(moret)::value, BGI = decltype(bgt)::value;
;             if (more) tile_load(kreg, K + (size_t)(64 * (t + 1)) * ldk, ldk, tid);
;             f32x16 st;
; #pragma unroll
;             for (int i = 0; i < 16; ++i) st[i] = 0.f;
;             if (DH == 128) {
;                 bf16x8 kfa[KS];
; #pragma unroll
;                 for (int s = 0; s < KS; ++s) kfa[s] = *(const LAS bf16x8*)(kbuf + ((32 * kh + r) * NCOMP + compA) * KST + (16 * s + 8 * h) * 2);
;                 asm volatile("" ::: "memory");
;                 tile_store_raw(vreg, vbuf, tid);
; #pragma unroll
;                 for (int s = 0; s < KS; ++s) st = MFMA32(kfa[s], qf[s], st);
;             } else {
;             tile_store_raw(vreg, vbuf, tid);
; #pragma unroll
;             for (int s = 0; s < KS; ++s) { const bf16x8 kf = *(const LAS bf16x8*)(kbuf + ((32 * kh + r) * NCOMP + compA) * KST + (16 * s + 8 * h) * 2); st = MFMA32(kf, qf[s], st);
;                 if ((s & 3) == 3) asm volatile("" ::: "memory"); }
;             }
;             float pe[16];
; #pragma unroll
;             for (int i = 0; i < 16; ++i) { pe[i] = fexp2(st[i] - m2); lsum += pe[i]; }
; #pragma unroll
;             for (int g = 0; g < 4; ++g) { u32x2 w; w.x = pk2(pe[4 * g], pe[4 * g + 1]); w.y = pk2(pe[4 * g + 2], pe[4 * g + 3]);
;                 *(LAS u32x2*)(pbuf + ((compA * NRB + rbA) * 32 + r) * PST + (32 * kh + 8 * g + 4 * h) * 2) = w; }
;             __syncthreads();
;             if (more) tile_load(vreg, V + (size_t)(64 * (t + 1)) * ldv, ldv, tid);
; #pragma unroll
;             for (int s = 0; s < 4; ++s) {
;                 bf16x8 pf[NCOMP];
; #pragma unroll
;                 for (int c = 0; c < NCOMP; ++c) pf[c] = *(const LAS bf16x8*)(pbuf + ((c * NRB + rbB) * 32 + r) * PST + (16 * s + 8 * h) * 2);
; #pragma unroll
;                 for (int b = 0; b < NBLK; ++b) {
;                     const bf16x8 vf = trfrag(vbuf + (16 * s + 8 * h + q4) * VST + (DVW * dvp + 32 * b + 16 * b16 + 4 * p4) * 2, 4 * VST);
; #pragma unroll
;                     for (int c = 0; c < NCOMP; ++c) O[c][b] = MFMA32(pf[c], vf, O[c][b]);
;                 }
.Lfa_loop_s2:
	ds_read_b128 v[202:205], v156
	ds_read_b128 v[206:209], v156 offset:32
	ds_read_b128 v[210:213], v156 offset:64
	ds_read_b128 v[214:217], v156 offset:96
	ds_read_b128 v[218:221], v156 offset:128
	ds_read_b128 v[222:225], v156 offset:160
	ds_read_b128 v[226:229], v156 offset:192
	ds_read_b128 v[230:233], v156 offset:224
	s_waitcnt vmcnt(12)
	ds_write_b128 v175, v[140:143]
	ds_write_b128 v175, v[144:147] offset:128
	ds_write_b128 v175, v[148:151] offset:256
	ds_write_b128 v175, v[152:155] offset:384
	s_add_i32 s16, s74, 3
	s_min_u32 s16, s16, s73
	s_lshl_b32 s16, s16, 6
	v_mad_i64_i32 v[250:251], s[76:77], s16, v166, v[178:179]
	global_load_dwordx4 v[140:143], v[250:251], off
	global_load_dwordx4 v[144:147], v[250:251], off offset:128
	global_load_dwordx4 v[148:151], v[250:251], off offset:256
	global_load_dwordx4 v[152:155], v[250:251], off offset:384
	s_waitcnt lgkmcnt(11)
	v_mfma_f32_32x32x16_bf16 v[68:83], v[202:205], v[112:115], 0
	s_waitcnt lgkmcnt(10)
	v_mfma_f32_32x32x16_bf16 v[68:83], v[206:209], v[108:111], v[68:83]
	s_waitcnt lgkmcnt(9)
	v_mfma_f32_32x32x16_bf16 v[68:83], v[210:213], v[104:107], v[68:83]
	s_waitcnt lgkmcnt(8)
	v_mfma_f32_32x32x16_bf16 v[68:83], v[214:217], v[100:103], v[68:83]
	s_waitcnt lgkmcnt(7)
	v_mfma_f32_32x32x16_bf16 v[68:83], v[218:221], v[96:99], v[68:83]
	s_waitcnt lgkmcnt(6)
	v_mfma_f32_32x32x16_bf16 v[68:83], v[222:225], v[92:95], v[68:83]
	s_waitcnt lgkmcnt(5)
	v_mfma_f32_32x32x16_bf16 v[68:83], v[226:229], v[88:91], v[68:83]
	s_waitcnt lgkmcnt(4)
	v_mfma_f32_32x32x16_bf16 v[68:83], v[230:233], v[84:87], v[68:83]
	s_barrier
	ds_read_b128 v[218:221], v180
	ds_read_b64_tr_b16 v[226:227], v183
	ds_read_b64_tr_b16 v[228:229], v183 offset:2304
	ds_read_b128 v[222:225], v180 offset:9216
	ds_read_b64_tr_b16 v[230:231], v183 offset:64
	ds_read_b64_tr_b16 v[232:233], v183 offset:2368
	ds_read_b128 v[202:205], v180 offset:32
	ds_read_b64_tr_b16 v[210:211], v183 offset:9216
	ds_read_b64_tr_b16 v[212:213], v183 offset:11520
	ds_read_b128 v[206:209], v180 offset:9248
	ds_read_b64_tr_b16 v[214:215], v183 offset:9280
	ds_read_b64_tr_b16 v[216:217], v183 offset:11584
	s_waitcnt lgkmcnt(9)
	v_mfma_f32_32x32x16_bf16 v[52:67], v[218:221], v[226:229], v[52:67]
	v_sub_f32_e32 v68, v68, v172
	v_sub_f32_e32 v69, v69, v172
	v_sub_f32_e32 v70, v70, v172
	v_sub_f32_e32 v71, v71, v172
	s_waitcnt lgkmcnt(8)
	v_mfma_f32_32x32x16_bf16 v[20:35], v[222:225], v[226:229], v[20:35]
	v_sub_f32_e32 v72, v72, v172
	v_sub_f32_e32 v73, v73, v172
	v_sub_f32_e32 v74, v74, v172
	v_sub_f32_e32 v75, v75, v172
	s_waitcnt lgkmcnt(6)
	v_mfma_f32_32x32x16_bf16 v[36:51], v[218:221], v[230:233], v[36:51]
	v_sub_f32_e32 v76, v76, v172
	v_sub_f32_e32 v77, v77, v172
	v_sub_f32_e32 v78, v78, v172
	v_sub_f32_e32 v79, v79, v172
	v_mfma_f32_32x32x16_bf16 v[4:19], v[222:225], v[230:233], v[4:19]
	v_sub_f32_e32 v80, v80, v172
	v_sub_f32_e32 v81, v81, v172
	v_sub_f32_e32 v82, v82, v172
	v_sub_f32_e32 v83, v83, v172
	ds_read_b128 v[218:221], v180 offset:64
	ds_read_b64_tr_b16 v[226:227], v183 offset:18432
	ds_read_b64_tr_b16 v[228:229], v183 offset:20736
	ds_read_b128 v[222:225], v180 offset:9280
	ds_read_b64_tr_b16 v[230:231], v183 offset:18496
	ds_read_b64_tr_b16 v[232:233], v183 offset:20800
	s_waitcnt lgkmcnt(9)
	v_mfma_f32_32x32x16_bf16 v[52:67], v[202:205], v[210:213], v[52:67]
	v_exp_f32_e32 v68, v68
	v_exp_f32_e32 v69, v69
	v_exp_f32_e32 v70, v70
	v_exp_f32_e32 v71, v71
	s_waitcnt lgkmcnt(8)
	v_mfma_f32_32x32x16_bf16 v[20:35], v[206:209], v[210:213], v[20:35]
	v_exp_f32_e32 v72, v72
	v_exp_f32_e32 v73, v73
	v_exp_f32_e32 v74, v74
	v_exp_f32_e32 v75, v75
	s_waitcnt lgkmcnt(6)
	v_mfma_f32_32x32x16_bf16 v[36:51], v[202:205], v[214:217], v[36:51]
	v_exp_f32_e32 v76, v76
	v_exp_f32_e32 v77, v77
	v_exp_f32_e32 v78, v78
	v_exp_f32_e32 v79, v79
	v_mfma_f32_32x32x16_bf16 v[4:19], v[206:209], v[214:217], v[4:19]
	v_exp_f32_e32 v80, v80
	v_exp_f32_e32 v81, v81
	v_exp_f32_e32 v82, v82
	v_exp_f32_e32 v83, v83
	ds_read_b128 v[202:205], v180 offset:96
	ds_read_b64_tr_b16 v[210:211], v183 offset:27648
	ds_read_b64_tr_b16 v[212:213], v183 offset:29952
	ds_read_b128 v[206:209], v180 offset:9312
	ds_read_b64_tr_b16 v[214:215], v183 offset:27712
	ds_read_b64_tr_b16 v[216:217], v183 offset:30016
	s_waitcnt lgkmcnt(9)
	v_mfma_f32_32x32x16_bf16 v[52:67], v[218:221], v[226:229], v[52:67]
	v_cvt_pk_bf16_f32 v132, v68, v69
	v_cvt_pk_bf16_f32 v133, v70, v71
	v_add_f32_e32 v182, v182, v68
	v_add_f32_e32 v182, v69, v182
	s_waitcnt lgkmcnt(8)
	v_mfma_f32_32x32x16_bf16 v[20:35], v[222:225], v[226:229], v[20:35]
	v_cvt_pk_bf16_f32 v134, v72, v73
	v_cvt_pk_bf16_f32 v135, v74, v75
	v_add_f32_e32 v182, v70, v182
	v_add_f32_e32 v182, v71, v182
	s_waitcnt lgkmcnt(6)
	v_mfma_f32_32x32x16_bf16 v[36:51], v[218:221], v[230:233], v[36:51]
	v_cvt_pk_bf16_f32 v136, v76, v77
	v_cvt_pk_bf16_f32 v137, v78, v79
	v_add_f32_e32 v182, v72, v182
	v_add_f32_e32 v182, v73, v182
	v_mfma_f32_32x32x16_bf16 v[4:19], v[222:225], v[230:233], v[4:19]
	v_cvt_pk_bf16_f32 v138, v80, v81
	v_cvt_pk_bf16_f32 v139, v82, v83
	v_add_f32_e32 v182, v74, v182
	v_add_f32_e32 v182, v75, v182
	ds_write2_b64 v177, v[132:133], v[134:135] offset1:2
	ds_write2_b64 v177, v[136:137], v[138:139] offset0:4 offset1:6
	s_waitcnt lgkmcnt(5)
	v_mfma_f32_32x32x16_bf16 v[52:67], v[202:205], v[210:213], v[52:67]
	v_add_f32_e32 v182, v76, v182
	v_add_f32_e32 v182, v77, v182
	s_waitcnt lgkmcnt(4)
	v_mfma_f32_32x32x16_bf16 v[20:35], v[206:209], v[210:213], v[20:35]
	v_add_f32_e32 v182, v78, v182
	v_add_f32_e32 v182, v79, v182
	s_waitcnt lgkmcnt(2)
	v_mfma_f32_32x32x16_bf16 v[36:51], v[202:205], v[214:217], v[36:51]
	v_add_f32_e32 v182, v80, v182
	v_add_f32_e32 v182, v81, v182
	v_mfma_f32_32x32x16_bf16 v[4:19], v[206:209], v[214:217], v[4:19]
	v_add_f32_e32 v182, v82, v182
	v_add_f32_e32 v182, v83, v182
	s_waitcnt vmcnt(12)
	ds_write_b128 v158, v[186:189]
	ds_write_b128 v158, v[190:193] offset:128
	ds_write_b128 v158, v[194:197] offset:272
	ds_write_b128 v158, v[198:201] offset:400
	s_add_i32 s16, s74, 4
	s_min_u32 s16, s16, s73
	s_lshl_b32 s16, s16, 6
	v_mad_i64_i32 v[250:251], s[76:77], s16, v166, v[160:161]
	global_load_dwordx4 v[186:189], v[250:251], off
	global_load_dwordx4 v[190:193], v[250:251], off offset:128
	global_load_dwordx4 v[194:197], v[250:251], off offset:256
	global_load_dwordx4 v[198:201], v[250:251], off offset:384
	s_waitcnt lgkmcnt(0)
	s_barrier
;     template <bool BG = false>
;     __device__ __forceinline__ void run(LAS unsigned char* lds, f32x16 (&O)[NCOMP][NBLK], BgConv* bg = nullptr) const {
;     ...
;         auto body = [&](const int t, auto moret, auto bgt) {
;             constexpr bool more = decltype(moret)::value, BGI = decltype(bgt)::value;
;             if (more) tile_load(kreg, K + (size_t)(64 * (t + 1)) * ldk, ldk, tid);
;             f32x16 st;
; #pragma unroll
;             for (int i = 0; i < 16; ++i) st[i] = 0.f;
;             if (DH == 128) {
;                 bf16x8 kfa[KS];
; #pragma unroll
;                 for (int s = 0; s < KS; ++s) kfa[s] = *(const LAS bf16x8*)(kbuf + ((32 * kh + r) * NCOMP + compA) * KST + (16 * s + 8 * h) * 2);
;                 asm volatile("" ::: "memory");
;                 tile_store_raw(vreg, vbuf, tid);
; #pragma unroll
;                 for (int s = 0; s < KS; ++s) st = MFMA32(kfa[s], qf[s], st);
;             } else {
;             tile_store_raw(vreg, vbuf, tid);
; #pragma unroll
;             for (int s = 0; s < KS; ++s) { const bf16x8 kf = *(const LAS bf16x8*)(kbuf + ((32 * kh + r) * NCOMP + compA) * KST + (16 * s + 8 * h) * 2); st = MFMA32(kf, qf[s], st);
;                 if ((s & 3) == 3) asm volatile("" ::: "memory"); }
;             }
;             float pe[16];
; #pragma unroll
;             for (int i = 0; i < 16; ++i) { pe[i] = fexp2(st[i] - m2); lsum += pe[i]; }
; #pragma unroll
;             for (int g = 0; g < 4; ++g) { u32x2 w; w.x = pk2(pe[4 * g], pe[4 * g + 1]); w.y = pk2(pe[4 * g + 2], pe[4 * g + 3]);
;                 *(LAS u32x2*)(pbuf + ((compA * NRB + rbA) * 32 + r) * PST + (32 * kh + 8 * g + 4 * h) * 2) = w; }
;             __syncthreads();
;             if (more) tile_load(vreg, V + (size_t)(64 * (t + 1)) * ldv, ldv, tid);
; #pragma unroll
;             for (int s = 0; s < 4; ++s) {
;                 bf16x8 pf[NCOMP];
; #pragma unroll
;                 for (int c = 0; c < NCOMP; ++c) pf[c] = *(const LAS bf16x8*)(pbuf + ((c * NRB + rbB) * 32 + r) * PST + (16 * s + 8 * h) * 2);
; #pragma unroll
;                 for (int b = 0; b < NBLK; ++b) {
;                     const bf16x8 vf = trfrag(vbuf + (16 * s + 8 * h + q4) * VST + (DVW * dvp + 32 * b + 16 * b16 + 4 * p4) * 2, 4 * VST);
; #pragma unroll
;                     for (int c = 0; c < NCOMP; ++c) O[c][b] = MFMA32(pf[c], vf, O[c][b]);
;                 }
	v_swap_b32 v173, v175
	v_swap_b32 v176, v177
	v_swap_b32 v180, v181
	v_swap_b32 v183, v184
	s_add_i32 s74, s74, 1
	s_cmp_lt_u32 s74, s73
	s_cbranch_scc0 .Lfa_fin_s2
	ds_read_b128 v[202:205], v156
	ds_read_b128 v[206:209], v156 offset:32
	ds_read_b128 v[210:213], v156 offset:64
	ds_read_b128 v[214:217], v156 offset:96
	ds_read_b128 v[218:221], v156 offset:128
	ds_read_b128 v[222:225], v156 offset:160
	ds_read_b128 v[226:229], v156 offset:192
	ds_read_b128 v[230:233], v156 offset:224
	s_waitcnt vmcnt(12)
	ds_write_b128 v175, v[128:131]
	ds_write_b128 v175, v[124:127] offset:128
	ds_write_b128 v175, v[120:123] offset:256
	ds_write_b128 v175, v[116:119] offset:384
	s_add_i32 s16, s74, 3
	s_min_u32 s16, s16, s73
	s_lshl_b32 s16, s16, 6
	v_mad_i64_i32 v[250:251], s[76:77], s16, v166, v[178:179]
	global_load_dwordx4 v[128:131], v[250:251], off
	global_load_dwordx4 v[124:127], v[250:251], off offset:128
	global_load_dwordx4 v[120:123], v[250:251], off offset:256
	global_load_dwordx4 v[116:119], v[250:251], off offset:384
	s_waitcnt lgkmcnt(11)
	v_mfma_f32_32x32x16_bf16 v[68:83], v[202:205], v[112:115], 0
	s_waitcnt lgkmcnt(10)
	v_mfma_f32_32x32x16_bf16 v[68:83], v[206:209], v[108:111], v[68:83]
	s_waitcnt lgkmcnt(9)
	v_mfma_f32_32x32x16_bf16 v[68:83], v[210:213], v[104:107], v[68:83]
	s_waitcnt lgkmcnt(8)
	v_mfma_f32_32x32x16_bf16 v[68:83], v[214:217], v[100:103], v[68:83]
	s_waitcnt lgkmcnt(7)
	v_mfma_f32_32x32x16_bf16 v[68:83], v[218:221], v[96:99], v[68:83]
	s_waitcnt lgkmcnt(6)
	v_mfma_f32_32x32x16_bf16 v[68:83], v[222:225], v[92:95], v[68:83]
	s_waitcnt lgkmcnt(5)
	v_mfma_f32_32x32x16_bf16 v[68:83], v[226:229], v[88:91], v[68:83]
	s_waitcnt lgkmcnt(4)
	v_mfma_f32_32x32x16_bf16 v[68:83], v[230:233], v[84:87], v[68:83]
	s_barrier
	ds_read_b128 v[218:221], v180
	ds_read_b64_tr_b16 v[226:227], v183
	ds_read_b64_tr_b16 v[228:229], v183 offset:2304
	ds_read_b128 v[222:225], v180 offset:9216
	ds_read_b64_tr_b16 v[230:231], v183 offset:64
	ds_read_b64_tr_b16 v[232:233], v183 offset:2368
	ds_read_b128 v[202:205], v180 offset:32
	ds_read_b64_tr_b16 v[210:211], v183 offset:9216
	ds_read_b64_tr_b16 v[212:213], v183 offset:11520
	ds_read_b128 v[206:209], v180 offset:9248
	ds_read_b64_tr_b16 v[214:215], v183 offset:9280
	ds_read_b64_tr_b16 v[216:217], v183 offset:11584
	s_waitcnt lgkmcnt(9)
	v_mfma_f32_32x32x16_bf16 v[52:67], v[218:221], v[226:229], v[52:67]
	v_sub_f32_e32 v68, v68, v172
	v_sub_f32_e32 v69, v69, v172
	v_sub_f32_e32 v70, v70, v172
	v_sub_f32_e32 v71, v71, v172
	s_waitcnt lgkmcnt(8)
	v_mfma_f32_32x32x16_bf16 v[20:35], v[222:225], v[226:229], v[20:35]
	v_sub_f32_e32 v72, v72, v172
	v_sub_f32_e32 v73, v73, v172
	v_sub_f32_e32 v74, v74, v172
	v_sub_f32_e32 v75, v75, v172
	s_waitcnt lgkmcnt(6)
	v_mfma_f32_32x32x16_bf16 v[36:51], v[218:221], v[230:233], v[36:51]
	v_sub_f32_e32 v76, v76, v172
	v_sub_f32_e32 v77, v77, v172
	v_sub_f32_e32 v78, v78, v172
	v_sub_f32_e32 v79, v79, v172
	v_mfma_f32_32x32x16_bf16 v[4:19], v[222:225], v[230:233], v[4:19]
	v_sub_f32_e32 v80, v80, v172
	v_sub_f32_e32 v81, v81, v172
	v_sub_f32_e32 v82, v82, v172
	v_sub_f32_e32 v83, v83, v172
	ds_read_b128 v[218:221], v180 offset:64
	ds_read_b64_tr_b16 v[226:227], v183 offset:18432
	ds_read_b64_tr_b16 v[228:229], v183 offset:20736
	ds_read_b128 v[222:225], v180 offset:9280
	ds_read_b64_tr_b16 v[230:231], v183 offset:18496
	ds_read_b64_tr_b16 v[232:233], v183 offset:20800
	s_waitcnt lgkmcnt(9)
	v_mfma_f32_32x32x16_bf16 v[52:67], v[202:205], v[210:213], v[52:67]
	v_exp_f32_e32 v68, v68
	v_exp_f32_e32 v69, v69
	v_exp_f32_e32 v70, v70
	v_exp_f32_e32 v71, v71
	s_waitcnt lgkmcnt(8)
	v_mfma_f32_32x32x16_bf16 v[20:35], v[206:209], v[210:213], v[20:35]
	v_exp_f32_e32 v72, v72
	v_exp_f32_e32 v73, v73
	v_exp_f32_e32 v74, v74
	v_exp_f32_e32 v75, v75
	s_waitcnt lgkmcnt(6)
	v_mfma_f32_32x32x16_bf16 v[36:51], v[202:205], v[214:217], v[36:51]
	v_exp_f32_e32 v76, v76
	v_exp_f32_e32 v77, v77
	v_exp_f32_e32 v78, v78
	v_exp_f32_e32 v79, v79
	v_mfma_f32_32x32x16_bf16 v[4:19], v[206:209], v[214:217], v[4:19]
	v_exp_f32_e32 v80, v80
	v_exp_f32_e32 v81, v81
	v_exp_f32_e32 v82, v82
	v_exp_f32_e32 v83, v83
	ds_read_b128 v[202:205], v180 offset:96
	ds_read_b64_tr_b16 v[210:211], v183 offset:27648
	ds_read_b64_tr_b16 v[212:213], v183 offset:29952
	ds_read_b128 v[206:209], v180 offset:9312
	ds_read_b64_tr_b16 v[214:215], v183 offset:27712
	ds_read_b64_tr_b16 v[216:217], v183 offset:30016
	s_waitcnt lgkmcnt(9)
	v_mfma_f32_32x32x16_bf16 v[52:67], v[218:221], v[226:229], v[52:67]
	v_cvt_pk_bf16_f32 v132, v68, v69
	v_cvt_pk_bf16_f32 v133, v70, v71
	v_add_f32_e32 v182, v182, v68
	v_add_f32_e32 v182, v69, v182
	s_waitcnt lgkmcnt(8)
	v_mfma_f32_32x32x16_bf16 v[20:35], v[222:225], v[226:229], v[20:35]
	v_cvt_pk_bf16_f32 v134, v72, v73
	v_cvt_pk_bf16_f32 v135, v74, v75
	v_add_f32_e32 v182, v70, v182
	v_add_f32_e32 v182, v71, v182
	s_waitcnt lgkmcnt(6)
	v_mfma_f32_32x32x16_bf16 v[36:51], v[218:221], v[230:233], v[36:51]
	v_cvt_pk_bf16_f32 v136, v76, v77
	v_cvt_pk_bf16_f32 v137, v78, v79
	v_add_f32_e32 v182, v72, v182
	v_add_f32_e32 v182, v73, v182
	v_mfma_f32_32x32x16_bf16 v[4:19], v[222:225], v[230:233], v[4:19]
	v_cvt_pk_bf16_f32 v138, v80, v81
	v_cvt_pk_bf16_f32 v139, v82, v83
	v_add_f32_e32 v182, v74, v182
	v_add_f32_e32 v182, v75, v182
	ds_write2_b64 v177, v[132:133], v[134:135] offset1:2
	ds_write2_b64 v177, v[136:137], v[138:139] offset0:4 offset1:6
	s_waitcnt lgkmcnt(5)
	v_mfma_f32_32x32x16_bf16 v[52:67], v[202:205], v[210:213], v[52:67]
	v_add_f32_e32 v182, v76, v182
	v_add_f32_e32 v182, v77, v182
	s_waitcnt lgkmcnt(4)
	v_mfma_f32_32x32x16_bf16 v[20:35], v[206:209], v[210:213], v[20:35]
	v_add_f32_e32 v182, v78, v182
	v_add_f32_e32 v182, v79, v182
	s_waitcnt lgkmcnt(2)
	v_mfma_f32_32x32x16_bf16 v[36:51], v[202:205], v[214:217], v[36:51]
	v_add_f32_e32 v182, v80, v182
	v_add_f32_e32 v182, v81, v182
	v_mfma_f32_32x32x16_bf16 v[4:19], v[206:209], v[214:217], v[4:19]
	v_add_f32_e32 v182, v82, v182
	v_add_f32_e32 v182, v83, v182
	s_waitcnt vmcnt(12)
	ds_write_b128 v158, v[234:237]
	ds_write_b128 v158, v[238:241] offset:128
	ds_write_b128 v158, v[242:245] offset:272
	ds_write_b128 v158, v[246:249] offset:400
	s_add_i32 s16, s74, 4
	s_min_u32 s16, s16, s73
	s_lshl_b32 s16, s16, 6
	v_mad_i64_i32 v[250:251], s[76:77], s16, v166, v[160:161]
	global_load_dwordx4 v[234:237], v[250:251], off
	global_load_dwordx4 v[238:241], v[250:251], off offset:128
	global_load_dwordx4 v[242:245], v[250:251], off offset:256
	global_load_dwordx4 v[246:249], v[250:251], off offset:384
	s_waitcnt lgkmcnt(0)
	s_barrier
	v_swap_b32 v173, v175
	v_swap_b32 v176, v177
	v_swap_b32 v180, v181
	v_swap_b32 v183, v184
	s_add_i32 s74, s74, 1
	s_cmp_lt_u32 s74, s73
	s_cbranch_scc1 .Lfa_loop_s2
; #define LAS __attribute__((address_space(3)))
; #define MFMA32(a, b, c) __builtin_amdgcn_mfma_f32_32x32x16_bf16((a), (b), (c), 0, 0, 0)
;     template <bool BG = false>
;     __device__ __forceinline__ void run(LAS unsigned char* lds, f32x16 (&O)[NCOMP][NBLK], BgConv* bg = nullptr) const {
;     ...
;             for (int s = 0; s < 4; ++s) {
;                 bf16x8 pf[NCOMP];
; #pragma unroll
;                 for (int c = 0; c < NCOMP; ++c) pf[c] = *(const LAS bf16x8*)(pbuf + ((c * NRB + rbB) * 32 + r) * PST + (16 * s + 8 * h) * 2);
; #pragma unroll
;                 for (int b = 0; b < NBLK; ++b) {
;                     const bf16x8 vf = trfrag(vbuf + (16 * s + 8 * h + q4) * VST + (DVW * dvp + 32 * b + 16 * b16 + 4 * p4) * 2, 4 * VST);
; #pragma unroll
;                     for (int c = 0; c < NCOMP; ++c) O[c][b] = MFMA32(pf[c], vf, O[c][b]);
;                 }
;                 asm volatile("" ::: "memory");
;                 if (DH == 128 && s == 1) { if (more) tile_store_k<DH, NCOMP>(kreg, kbuf, tid); }
;             }
;             if (DH != 128) { if (more) tile_store_k<DH, NCOMP>(kreg, kbuf, tid); }
;             if constexpr (BGI) { bg_store(*bg, bgv, bgg, lane); bg->h += bg->step; bg_load(*bg, bgv, bgg, lane); }
;             __syncthreads();
;         };
;         int t = 0;
;         if constexpr (BG) {
;             int n = 0; if (bg->h < BG_NH) { n = (BG_NH - 1 - bg->h) / bg->step + 1; const int fit = (ntiles - 1) / 2; n = (n < fit) ? n : fit; }
;             if (n > 0) { bg_load(*bg, bgv, bgg, lane);
; #pragma unroll 1
;                 for (int g = 0; g < n; ++g, t += 2) { body(t, BoolT<true>{}, BoolT<false>{}); body(t + 1, BoolT<true>{}, BoolT<true>{}); } } }
;         for (; t < ntiles - 1; ++t) body(t, BoolT<true>{}, BoolT<false>{});
;         body(ntiles - 1, BoolT<false>{}, BoolT<false>{});
;         lsum += __shfl_xor(lsum, 32);
;         if (h == 0) lbuf[((compA * NRB + rbA) * 2 + kh) * 32 + r] = lsum;
.Lfa_fin_s2:
	ds_read_b128 v[218:221], v180
	ds_read_b64_tr_b16 v[226:227], v183
	ds_read_b64_tr_b16 v[228:229], v183 offset:2304
	ds_read_b128 v[222:225], v180 offset:9216
	ds_read_b64_tr_b16 v[230:231], v183 offset:64
	ds_read_b64_tr_b16 v[232:233], v183 offset:2368
	ds_read_b128 v[202:205], v180 offset:32
	ds_read_b64_tr_b16 v[210:211], v183 offset:9216
	ds_read_b64_tr_b16 v[212:213], v183 offset:11520
	ds_read_b128 v[206:209], v180 offset:9248
	ds_read_b64_tr_b16 v[214:215], v183 offset:9280
	ds_read_b64_tr_b16 v[216:217], v183 offset:11584
	s_waitcnt lgkmcnt(9)
	v_mfma_f32_32x32x16_bf16 v[52:67], v[218:221], v[226:229], v[52:67]
	s_waitcnt lgkmcnt(8)
	v_mfma_f32_32x32x16_bf16 v[20:35], v[222:225], v[226:229], v[20:35]
	s_waitcnt lgkmcnt(6)
	v_mfma_f32_32x32x16_bf16 v[36:51], v[218:221], v[230:233], v[36:51]
	v_mfma_f32_32x32x16_bf16 v[4:19], v[222:225], v[230:233], v[4:19]
	ds_read_b128 v[218:221], v180 offset:64
	ds_read_b64_tr_b16 v[226:227], v183 offset:18432
	ds_read_b64_tr_b16 v[228:229], v183 offset:20736
	ds_read_b128 v[222:225], v180 offset:9280
	ds_read_b64_tr_b16 v[230:231], v183 offset:18496
	ds_read_b64_tr_b16 v[232:233], v183 offset:20800
	s_waitcnt lgkmcnt(9)
	v_mfma_f32_32x32x16_bf16 v[52:67], v[202:205], v[210:213], v[52:67]
	s_waitcnt lgkmcnt(8)
	v_mfma_f32_32x32x16_bf16 v[20:35], v[206:209], v[210:213], v[20:35]
	s_waitcnt lgkmcnt(6)
	v_mfma_f32_32x32x16_bf16 v[36:51], v[202:205], v[214:217], v[36:51]
	v_mfma_f32_32x32x16_bf16 v[4:19], v[206:209], v[214:217], v[4:19]
	ds_read_b128 v[202:205], v180 offset:96
	ds_read_b64_tr_b16 v[210:211], v183 offset:27648
	ds_read_b64_tr_b16 v[212:213], v183 offset:29952
	ds_read_b128 v[206:209], v180 offset:9312
	ds_read_b64_tr_b16 v[214:215], v183 offset:27712
	ds_read_b64_tr_b16 v[216:217], v183 offset:30016
	s_waitcnt lgkmcnt(9)
	v_mfma_f32_32x32x16_bf16 v[52:67], v[218:221], v[226:229], v[52:67]
	s_waitcnt lgkmcnt(8)
	v_mfma_f32_32x32x16_bf16 v[20:35], v[222:225], v[226:229], v[20:35]
	s_waitcnt lgkmcnt(6)
	v_mfma_f32_32x32x16_bf16 v[36:51], v[218:221], v[230:233], v[36:51]
	v_mfma_f32_32x32x16_bf16 v[4:19], v[222:225], v[230:233], v[4:19]
	s_waitcnt lgkmcnt(3)
	v_mfma_f32_32x32x16_bf16 v[52:67], v[202:205], v[210:213], v[52:67]
	s_waitcnt lgkmcnt(2)
	v_mfma_f32_32x32x16_bf16 v[20:35], v[206:209], v[210:213], v[20:35]
	s_waitcnt lgkmcnt(0)
	v_mfma_f32_32x32x16_bf16 v[36:51], v[202:205], v[214:217], v[36:51]
	v_mfma_f32_32x32x16_bf16 v[4:19], v[206:209], v[214:217], v[4:19]
	s_waitcnt vmcnt(0)
	s_nop 15
	v_mov_b32_e32 v2, v182
	ds_bpermute_b32 v68, v170, v2
	v_cmp_gt_u32_e32 vcc, 32, v174
	s_and_saveexec_b64 s[26:27], vcc
	s_cbranch_execz .LBB0_777
	s_lshl_b32 s16, s36, 2
	s_lshl_b32 s29, s37, 1
	s_add_i32 s16, s16, s29
	s_or_b32 s16, s16, s28
	s_lshl_b32 s16, s16, 7
	s_add_i32 s16, s16, 0
	v_lshl_add_u32 v69, v171, 2, s16
	v_add_u32_e32 v69, 0x16800, v69
	s_waitcnt lgkmcnt(0)
	v_add_f32_e32 v2, v2, v68
	ds_write_b32 v69, v2
